# gmlp token-mixing MFMA section: three LDS reads kept in flight instead of read-wait-mfma per fragment
# baseline (speedup 1.0000x reference)
.LBB0_239:
	v_lshlrev_b64 v[32:33], 11, v[32:33]
	v_lshl_add_u64 v[112:113], s[84:85], 0, v[32:33]
	ds_read_b128 v[36:39], v133
	ds_read_b128 v[80:83], v133 offset:47872
	ds_read_b128 v[40:43], v133 offset:4352
	ds_read_b128 v[52:55], v133 offset:64
	ds_read_b128 v[44:47], v133 offset:8704
	ds_read_b128 v[48:51], v133 offset:13056
	ds_read_b128 v[72:75], v133 offset:39168
	ds_read_b128 v[76:79], v133 offset:43520
	s_mov_b64 s[18:19], 0x1a000600
	s_add_i32 s9, s9, s3
	s_add_i32 s20, s20, s0
	s_add_i32 s2, s2, s3
	s_cmpk_lt_i32 s9, 0x200
	s_waitcnt lgkmcnt(7)
	v_mfma_f32_16x16x32_bf16 v[36:39], v[36:39], v[164:167], 0
	ds_read_b128 v[60:63], v133 offset:26112
	ds_read_b128 v[68:71], v133 offset:17472
	s_waitcnt lgkmcnt(7)
	v_mfma_f32_16x16x32_bf16 v[40:43], v[40:43], v[164:167], 0
	ds_read_b128 v[64:67], v133 offset:30464
	ds_read_b128 v[56:59], v133 offset:21760
	ds_read_b128 v[84:87], v133 offset:34880
	s_waitcnt lgkmcnt(8)
	v_mfma_f32_16x16x32_bf16 v[44:47], v[44:47], v[164:167], 0
	ds_read_b128 v[154:157], v133 offset:65280
	ds_read_b128 v[158:161], v133 offset:52288
	ds_read_b128 v[92:95], v133 offset:60928
	s_waitcnt lgkmcnt(10)
	v_mfma_f32_16x16x32_bf16 v[32:35], v[48:51], v[164:167], 0
	v_mfma_f32_16x16x32_bf16 v[36:39], v[52:55], v[172:175], v[36:39]
	ds_read_b128 v[100:103], v133 offset:4416
	ds_read_b128 v[104:107], v133 offset:8768
	ds_read_b128 v[246:249], v133 offset:13120
	s_waitcnt lgkmcnt(2)
	v_mfma_f32_16x16x32_bf16 v[40:43], v[100:103], v[172:175], v[40:43]
	ds_read_b128 v[100:103], v133 offset:128
	s_waitcnt lgkmcnt(2)
	v_mfma_f32_16x16x32_bf16 v[44:47], v[104:107], v[172:175], v[44:47]
	ds_read_b128 v[104:107], v133 offset:4480
	s_waitcnt lgkmcnt(2)
	v_mfma_f32_16x16x32_bf16 v[32:35], v[246:249], v[172:175], v[32:35]
	ds_read_b128 v[246:249], v133 offset:8832
	s_waitcnt lgkmcnt(2)
	v_mfma_f32_16x16x32_bf16 v[36:39], v[100:103], v[176:179], v[36:39]
	ds_read_b128 v[100:103], v133 offset:13184
	s_waitcnt lgkmcnt(2)
	v_mfma_f32_16x16x32_bf16 v[40:43], v[104:107], v[176:179], v[40:43]
	ds_read_b128 v[104:107], v133 offset:192
	s_waitcnt lgkmcnt(2)
	v_mfma_f32_16x16x32_bf16 v[52:55], v[246:249], v[176:179], v[44:47]
	ds_read_b128 v[246:249], v133 offset:4544
	s_nop 2
	s_waitcnt lgkmcnt(2)
	v_mfma_f32_16x16x32_bf16 v[32:35], v[100:103], v[176:179], v[32:35]
	ds_read_b128 v[100:103], v133 offset:8896
	s_waitcnt lgkmcnt(2)
	v_mfma_f32_16x16x32_bf16 v[44:47], v[104:107], v[180:183], v[36:39]
	ds_read_b128 v[104:107], v133 offset:13248
	s_nop 2
	s_nop 3
	v_pk_add_f32 v[44:45], v[234:235], v[44:45] op_sel_hi:[0,1]
	s_waitcnt lgkmcnt(2)
	v_mfma_f32_16x16x32_bf16 v[40:43], v[246:249], v[180:183], v[40:43]
	ds_read_b128 v[246:249], v133 offset:17408
	v_pk_add_f32 v[46:47], v[234:235], v[46:47] op_sel_hi:[0,1]
	s_nop 5
	v_pk_add_f32 v[42:43], v[234:235], v[42:43] op_sel_hi:[0,1]
	s_waitcnt lgkmcnt(2)
	v_mfma_f32_16x16x32_bf16 v[36:39], v[100:103], v[180:183], v[52:55]
	ds_read_b128 v[100:103], v133 offset:21824
	s_nop 2
	v_pk_add_f32 v[40:41], v[234:235], v[40:41] op_sel_hi:[0,1]
	s_nop 2
	v_add_f32_e32 v37, v234, v37
	s_waitcnt lgkmcnt(2)
	v_mfma_f32_16x16x32_bf16 v[32:35], v[104:107], v[180:183], v[32:35]
	ds_read_b128 v[104:107], v133 offset:26176
	v_add_f32_e32 v38, v234, v38
	s_waitcnt lgkmcnt(2)
	v_mfma_f32_16x16x32_bf16 v[52:55], v[246:249], v[184:187], 0
	ds_read_b128 v[246:249], v133 offset:30528
	v_add_f32_e32 v36, v234, v36
	v_add_f32_e32 v39, v234, v39
	s_nop 0
	v_add_f32_e32 v32, v234, v32
	v_mfma_f32_16x16x32_bf16 v[56:59], v[56:59], v[184:187], 0
	v_add_f32_e32 v33, v234, v33
	v_mfma_f32_16x16x32_bf16 v[60:63], v[60:63], v[184:187], 0
	v_mfma_f32_16x16x32_bf16 v[48:51], v[64:67], v[184:187], 0
	v_mfma_f32_16x16x32_bf16 v[52:55], v[68:71], v[188:191], v[52:55]
	s_waitcnt lgkmcnt(2)
	v_mfma_f32_16x16x32_bf16 v[56:59], v[100:103], v[188:191], v[56:59]
	ds_read_b128 v[100:103], v133 offset:17536
	s_waitcnt lgkmcnt(2)
	v_mfma_f32_16x16x32_bf16 v[60:63], v[104:107], v[188:191], v[60:63]
	ds_read_b128 v[104:107], v133 offset:21888
	s_waitcnt lgkmcnt(2)
	v_mfma_f32_16x16x32_bf16 v[48:51], v[246:249], v[188:191], v[48:51]
	ds_read_b128 v[246:249], v133 offset:26240
	s_waitcnt lgkmcnt(2)
	v_mfma_f32_16x16x32_bf16 v[52:55], v[100:103], v[192:195], v[52:55]
	ds_read_b128 v[100:103], v133 offset:30592
	s_waitcnt lgkmcnt(2)
	v_mfma_f32_16x16x32_bf16 v[56:59], v[104:107], v[192:195], v[56:59]
	ds_read_b128 v[104:107], v133 offset:17600
	s_waitcnt lgkmcnt(2)
	v_mfma_f32_16x16x32_bf16 v[68:71], v[246:249], v[192:195], v[60:63]
	ds_read_b128 v[246:249], v133 offset:21952
	s_nop 2
	s_waitcnt lgkmcnt(2)
	v_mfma_f32_16x16x32_bf16 v[48:51], v[100:103], v[192:195], v[48:51]
	ds_read_b128 v[100:103], v133 offset:26304
	s_waitcnt lgkmcnt(2)
	v_mfma_f32_16x16x32_bf16 v[60:63], v[104:107], v[196:199], v[52:55]
	ds_read_b128 v[104:107], v133 offset:30656
	s_nop 2
	s_waitcnt lgkmcnt(2)
	v_mfma_f32_16x16x32_bf16 v[56:59], v[246:249], v[196:199], v[56:59]
	ds_read_b128 v[246:249], v133 offset:34816
	s_nop 6
	v_pk_add_f32 v[56:57], v[236:237], v[56:57] op_sel_hi:[0,1]
	s_waitcnt lgkmcnt(2)
	v_mfma_f32_16x16x32_bf16 v[52:55], v[100:103], v[196:199], v[68:71]
	ds_read_b128 v[100:103], v133 offset:39232
	s_nop 2
	v_pk_add_f32 v[58:59], v[236:237], v[58:59] op_sel_hi:[0,1]
	s_waitcnt lgkmcnt(2)
	v_mfma_f32_16x16x32_bf16 v[48:51], v[104:107], v[196:199], v[48:51]
	ds_read_b128 v[104:107], v133 offset:43584
	s_waitcnt lgkmcnt(2)
	v_mfma_f32_16x16x32_bf16 v[68:71], v[246:249], v[200:203], 0
	ds_read_b128 v[246:249], v133 offset:47936
	v_mfma_f32_16x16x32_bf16 v[72:75], v[72:75], v[200:203], 0
	v_mfma_f32_16x16x32_bf16 v[76:79], v[76:79], v[200:203], 0
	v_mfma_f32_16x16x32_bf16 v[64:67], v[80:83], v[200:203], 0
	v_mfma_f32_16x16x32_bf16 v[68:71], v[84:87], v[204:207], v[68:71]
	s_waitcnt lgkmcnt(2)
	v_mfma_f32_16x16x32_bf16 v[72:75], v[100:103], v[204:207], v[72:75]
	ds_read_b128 v[100:103], v133 offset:34944
	s_waitcnt lgkmcnt(2)
	v_mfma_f32_16x16x32_bf16 v[76:79], v[104:107], v[204:207], v[76:79]
	ds_read_b128 v[104:107], v133 offset:39296
	s_waitcnt lgkmcnt(2)
	v_mfma_f32_16x16x32_bf16 v[64:67], v[246:249], v[204:207], v[64:67]
	ds_read_b128 v[246:249], v133 offset:43648
	s_waitcnt lgkmcnt(2)
	v_mfma_f32_16x16x32_bf16 v[68:71], v[100:103], v[214:217], v[68:71]
	ds_read_b128 v[100:103], v133 offset:48000
	s_waitcnt lgkmcnt(2)
	v_mfma_f32_16x16x32_bf16 v[72:75], v[104:107], v[214:217], v[72:75]
	ds_read_b128 v[104:107], v133 offset:35008
	s_waitcnt lgkmcnt(2)
	v_mfma_f32_16x16x32_bf16 v[84:87], v[246:249], v[214:217], v[76:79]
	ds_read_b128 v[246:249], v133 offset:39360
	s_nop 2
	s_waitcnt lgkmcnt(2)
	v_mfma_f32_16x16x32_bf16 v[80:83], v[100:103], v[214:217], v[64:67]
	ds_read_b128 v[100:103], v133 offset:48064
	s_nop 2
	s_waitcnt lgkmcnt(2)
	v_mfma_f32_16x16x32_bf16 v[76:79], v[104:107], v[168:171], v[68:71]
	ds_read_b128 v[104:107], v133 offset:43712
	s_nop 1
	s_waitcnt lgkmcnt(1)
	v_mfma_f32_16x16x32_bf16 v[68:71], v[100:103], v[168:171], v[80:83]
	s_nop 2
	s_waitcnt lgkmcnt(2)
	v_mfma_f32_16x16x32_bf16 v[72:75], v[246:249], v[168:171], v[72:75]
	ds_read_b128 v[246:249], v133 offset:52224
	ds_read_b128 v[100:103], v133 offset:56576
	s_waitcnt lgkmcnt(2)
	v_mfma_f32_16x16x32_bf16 v[64:67], v[104:107], v[168:171], v[84:87]
	ds_read_b128 v[104:107], v133 offset:56640
	s_nop 2
	v_pk_add_f32 v[72:73], v[238:239], v[72:73] op_sel_hi:[0,1]
	s_waitcnt lgkmcnt(2)
	v_mfma_f32_16x16x32_bf16 v[84:87], v[246:249], v[218:221], 0
	ds_read_b128 v[246:249], v133 offset:60992
	v_add_f32_e64 v74, v238, v74
	v_add_f32_e64 v75, v238, v75
	s_waitcnt lgkmcnt(2)
	v_mfma_f32_16x16x32_bf16 v[88:91], v[100:103], v[218:221], 0
	ds_read_b128 v[100:103], v133 offset:65344
	v_mfma_f32_16x16x32_bf16 v[92:95], v[92:95], v[218:221], 0
	v_mfma_f32_16x16x32_bf16 v[80:83], v[154:157], v[218:221], 0
	v_mfma_f32_16x16x32_bf16 v[84:87], v[158:161], v[222:225], v[84:87]
	s_waitcnt lgkmcnt(2)
	v_mfma_f32_16x16x32_bf16 v[88:91], v[104:107], v[222:225], v[88:91]
	ds_read_b128 v[104:107], v133 offset:52352
	s_waitcnt lgkmcnt(2)
	v_mfma_f32_16x16x32_bf16 v[92:95], v[246:249], v[222:225], v[92:95]
	ds_read_b128 v[246:249], v133 offset:56704
	s_waitcnt lgkmcnt(2)
	v_mfma_f32_16x16x32_bf16 v[80:83], v[100:103], v[222:225], v[80:83]
	ds_read_b128 v[100:103], v133 offset:61056
	s_waitcnt lgkmcnt(2)
	v_mfma_f32_16x16x32_bf16 v[84:87], v[104:107], v[226:229], v[84:87]
	ds_read_b128 v[104:107], v133 offset:65408
	s_waitcnt lgkmcnt(2)
	v_mfma_f32_16x16x32_bf16 v[88:91], v[246:249], v[226:229], v[88:91]
	ds_read_b128 v[246:249], v133 offset:52416
	s_waitcnt lgkmcnt(2)
	v_mfma_f32_16x16x32_bf16 v[158:161], v[100:103], v[226:229], v[92:95]
	ds_read_b128 v[100:103], v133 offset:56768
	s_nop 2
	s_waitcnt lgkmcnt(2)
	v_mfma_f32_16x16x32_bf16 v[80:83], v[104:107], v[226:229], v[80:83]
	ds_read_b128 v[104:107], v133 offset:61120
	s_waitcnt lgkmcnt(2)
	v_mfma_f32_16x16x32_bf16 v[92:95], v[246:249], v[230:233], v[84:87]
	ds_read_b128 v[246:249], v133 offset:65472
	s_nop 2
	s_waitcnt lgkmcnt(2)
	v_mfma_f32_16x16x32_bf16 v[88:91], v[100:103], v[230:233], v[88:91]
	s_nop 6
	s_nop 0
	v_pk_add_f32 v[90:91], v[240:241], v[90:91] op_sel_hi:[0,1]
	s_waitcnt lgkmcnt(1)
	v_mfma_f32_16x16x32_bf16 v[84:87], v[104:107], v[230:233], v[158:161]
	s_nop 2
	v_pk_add_f32 v[88:89], v[240:241], v[88:89] op_sel_hi:[0,1]
	s_waitcnt lgkmcnt(0)
	v_mfma_f32_16x16x32_bf16 v[80:83], v[246:249], v[230:233], v[80:83]
	s_waitcnt vmcnt(0)
	v_lshlrev_b32_e32 v154, 16, v152
	v_and_b32_e32 v155, 0xffff0000, v152
	v_pk_mul_f32 v[44:45], v[44:45], v[154:155]
	v_lshlrev_b32_e32 v154, 16, v148
	v_and_b32_e32 v155, 0xffff0000, v148
	v_lshlrev_b32_e32 v148, 16, v149
	v_and_b32_e32 v149, 0xffff0000, v149
	v_pk_mul_f32 v[42:43], v[42:43], v[148:149]
	v_pk_mul_f32 v[40:41], v[40:41], v[154:155]
	v_mul_f32_e32 v148, v43, v43
	v_pk_fma_f32 v[154:155], v[42:43], v[42:43], v[148:149] op_sel_hi:[1,1,0]
	v_lshlrev_b32_e32 v148, 16, v146
	v_and_b32_e32 v146, 0xffff0000, v146
	v_mul_f32_e32 v146, v37, v146
	v_lshlrev_b32_e32 v37, 16, v147
	v_mul_f32_e32 v38, v38, v37
	v_and_b32_e32 v37, 0xffff0000, v147
	v_lshlrev_b32_e32 v152, 16, v153
	v_and_b32_e32 v153, 0xffff0000, v153
	v_mul_f32_e32 v36, v36, v148
	v_mul_f32_e32 v148, v39, v37
	v_lshlrev_b32_e32 v37, 16, v144
	v_pk_mul_f32 v[46:47], v[46:47], v[152:153]
	v_mul_f32_e32 v151, v32, v37
	v_and_b32_e32 v32, 0xffff0000, v144
	v_mul_f32_e32 v152, v47, v47
	v_mul_f32_e32 v33, v33, v32
	v_mul_f32_e32 v32, v45, v45
	v_pk_fma_f32 v[152:153], v[46:47], v[46:47], v[152:153] op_sel_hi:[1,1,0]
	v_pk_fma_f32 v[160:161], v[44:45], v[44:45], v[32:33] op_sel_hi:[1,1,0]
	v_add_f32_e32 v37, v234, v34
	v_add_f32_e32 v39, v234, v35
	v_mov_b32_e32 v150, v160
	v_mov_b32_e32 v162, v152
	v_mov_b32_e32 v163, v151
	v_pk_add_f32 v[152:153], v[160:161], v[152:153]
	v_pk_mul_f32 v[160:161], v[150:151], v[162:163]
	v_mul_f32_e32 v32, v41, v41
	v_mov_b32_e32 v153, v161
	v_pk_fma_f32 v[160:161], v[40:41], v[40:41], v[32:33] op_sel_hi:[1,1,0]
	v_mov_b32_e32 v162, v154
	v_mov_b32_e32 v32, v160
	v_mov_b32_e32 v163, v33
	v_lshlrev_b32_e32 v157, 16, v145
	v_mov_b32_e32 v156, v36
	v_pk_add_f32 v[154:155], v[160:161], v[154:155]
	v_pk_mul_f32 v[160:161], v[32:33], v[162:163]
	v_and_b32_e32 v159, 0xffff0000, v145
	v_pk_mul_f32 v[34:35], v[36:37], v[156:157]
	v_mov_b32_e32 v147, v37
	v_mov_b32_e32 v156, v146
	v_mov_b32_e32 v158, v38
	v_mov_b32_e32 v155, v161
	v_pk_mul_f32 v[144:145], v[38:39], v[158:159]
	v_mov_b32_e32 v149, v39
	v_mov_b32_e32 v158, v148
	v_pk_add_f32 v[152:153], v[152:153], v[154:155]
	v_pk_fma_f32 v[154:155], v[146:147], v[156:157], v[34:35]
	v_pk_mul_f32 v[156:157], v[34:35], v[34:35]
	v_add_f32_e32 v34, v236, v52
	v_mov_b32_e32 v155, v157
	v_pk_fma_f32 v[156:157], v[148:149], v[158:159], v[144:145]
	v_pk_mul_f32 v[158:159], v[144:145], v[144:145]
	v_and_b32_e32 v161, 0xffff0000, v135
	v_mov_b32_e32 v157, v159
	v_pk_add_f32 v[154:155], v[154:155], v[156:157]
	v_mov_b32_e32 v157, v62
	v_mov_b32_e32 v62, v61
	v_pk_add_f32 v[154:155], v[152:153], v[154:155]
	v_lshlrev_b32_e32 v153, 16, v141
	v_lshlrev_b32_e32 v152, 16, v140
	v_mov_b32_e32 v156, v60
	v_and_b32_e32 v141, 0xffff0000, v141
	v_and_b32_e32 v140, 0xffff0000, v140
	v_pk_add_f32 v[60:61], v[236:237], v[62:63] op_sel_hi:[0,1]
	v_pk_add_f32 v[156:157], v[236:237], v[156:157] op_sel_hi:[0,1]
	v_pk_mul_f32 v[60:61], v[60:61], v[140:141]
	v_pk_mul_f32 v[152:153], v[156:157], v[152:153]
	v_pk_mul_f32 v[62:63], v[60:61], v[60:61]
	v_pk_add_f32 v[154:155], v[154:155], v[154:155] op_sel:[0,1] op_sel_hi:[1,0]
	v_pk_fma_f32 v[62:63], v[152:153], v[152:153], v[62:63]
	v_lshlrev_b32_e32 v159, 16, v135
	v_pk_add_f32 v[140:141], v[62:63], v[62:63] op_sel:[0,1] op_sel_hi:[1,0]
	v_lshlrev_b32_e32 v62, 16, v138
	v_and_b32_e32 v63, 0xffff0000, v138
	v_pk_mul_f32 v[56:57], v[56:57], v[62:63]
	v_lshlrev_b32_e32 v62, 16, v139
	v_and_b32_e32 v63, 0xffff0000, v139
	v_pk_mul_f32 v[58:59], v[58:59], v[62:63]
	v_mov_b32_e32 v162, v140
	v_mul_f32_e32 v32, v59, v59
	v_pk_fma_f32 v[156:157], v[58:59], v[58:59], v[32:33] op_sel_hi:[1,1,0]
	v_lshlrev_b32_e32 v32, 16, v136
	v_mul_f32_e32 v52, v34, v32
	v_and_b32_e32 v32, 0xffff0000, v136
	v_add_f32_e32 v34, v236, v53
	v_mul_f32_e32 v62, v34, v32
	v_lshlrev_b32_e32 v32, 16, v137
	v_add_f32_e32 v34, v236, v54
	v_mul_f32_e32 v136, v34, v32
	v_and_b32_e32 v32, 0xffff0000, v137
	v_add_f32_e32 v34, v236, v55
	v_mul_f32_e32 v138, v34, v32
	v_lshlrev_b32_e32 v32, 16, v134
	v_add_f32_e32 v34, v236, v48
	v_mul_f32_e32 v55, v34, v32
	v_and_b32_e32 v32, 0xffff0000, v134
	v_add_f32_e32 v34, v236, v49
	v_mov_b32_e32 v54, v154
	v_mov_b32_e32 v163, v55
	v_mul_f32_e32 v49, v34, v32
	v_pk_add_f32 v[140:141], v[154:155], v[140:141]
	v_pk_mul_f32 v[154:155], v[54:55], v[162:163]
	v_mul_f32_e32 v32, v57, v57
	v_mov_b32_e32 v141, v155
	v_pk_fma_f32 v[154:155], v[56:57], v[56:57], v[32:33] op_sel_hi:[1,1,0]
	v_mov_b32_e32 v162, v156
	v_mov_b32_e32 v48, v154
	v_mov_b32_e32 v163, v49
	v_add_f32_e32 v53, v236, v50
	v_mov_b32_e32 v158, v52
	v_pk_add_f32 v[154:155], v[154:155], v[156:157]
	v_pk_mul_f32 v[156:157], v[48:49], v[162:163]
	v_add_f32_e32 v137, v236, v51
	v_pk_mul_f32 v[50:51], v[52:53], v[158:159]
	v_mov_b32_e32 v63, v53
	v_mov_b32_e32 v158, v62
	v_mov_b32_e32 v160, v136
	v_mov_b32_e32 v155, v157
	v_pk_mul_f32 v[134:135], v[136:137], v[160:161]
	v_mov_b32_e32 v139, v137
	v_mov_b32_e32 v160, v138
	v_pk_add_f32 v[140:141], v[140:141], v[154:155]
	v_pk_fma_f32 v[154:155], v[62:63], v[158:159], v[50:51]
	v_pk_mul_f32 v[156:157], v[50:51], v[50:51]
	v_pk_mul_f32 v[158:159], v[134:135], v[134:135]
	v_mov_b32_e32 v155, v157
	v_pk_fma_f32 v[156:157], v[138:139], v[160:161], v[134:135]
	v_add_f32_e32 v34, v238, v64
	v_mov_b32_e32 v157, v159
	v_pk_add_f32 v[154:155], v[154:155], v[156:157]
	v_mov_b32_e32 v157, v78
	v_mov_b32_e32 v78, v77
	v_pk_add_f32 v[154:155], v[140:141], v[154:155]
	v_lshlrev_b32_e32 v141, 16, v131
	v_lshlrev_b32_e32 v140, 16, v130
	v_mov_b32_e32 v156, v76
	v_and_b32_e32 v131, 0xffff0000, v131
	v_and_b32_e32 v130, 0xffff0000, v130
	v_pk_add_f32 v[76:77], v[238:239], v[78:79] op_sel_hi:[0,1]
	v_pk_add_f32 v[156:157], v[238:239], v[156:157] op_sel_hi:[0,1]
	v_pk_mul_f32 v[76:77], v[76:77], v[130:131]
	v_pk_mul_f32 v[140:141], v[156:157], v[140:141]
	v_pk_mul_f32 v[78:79], v[76:77], v[76:77]
	v_pk_add_f32 v[154:155], v[154:155], v[154:155] op_sel:[0,1] op_sel_hi:[1,0]
	v_pk_fma_f32 v[78:79], v[140:141], v[140:141], v[78:79]
	v_lshlrev_b32_e32 v159, 16, v125
	v_pk_add_f32 v[130:131], v[78:79], v[78:79] op_sel:[0,1] op_sel_hi:[1,0]
	v_lshlrev_b32_e32 v78, 16, v128
	v_and_b32_e32 v79, 0xffff0000, v128
	v_pk_mul_f32 v[72:73], v[72:73], v[78:79]
	v_lshlrev_b32_e32 v78, 16, v129
	v_and_b32_e32 v79, 0xffff0000, v129
	v_pk_mul_f32 v[74:75], v[74:75], v[78:79]
	v_mov_b32_e32 v162, v130
	v_mul_f32_e32 v32, v75, v75
	v_pk_fma_f32 v[156:157], v[74:75], v[74:75], v[32:33] op_sel_hi:[1,1,0]
	v_lshlrev_b32_e32 v32, 16, v126
	v_mul_f32_e32 v64, v34, v32
	v_and_b32_e32 v32, 0xffff0000, v126
	v_add_f32_e32 v34, v238, v65
	v_mul_f32_e32 v78, v34, v32
	v_lshlrev_b32_e32 v32, 16, v127
	v_add_f32_e32 v34, v238, v66
	v_mul_f32_e32 v126, v34, v32
	v_and_b32_e32 v32, 0xffff0000, v127
	v_add_f32_e32 v34, v238, v67
	v_mul_f32_e32 v128, v34, v32
	v_lshlrev_b32_e32 v32, 16, v124
	v_add_f32_e32 v34, v238, v68
	v_mul_f32_e32 v67, v34, v32
	v_and_b32_e32 v32, 0xffff0000, v124
	v_add_f32_e32 v34, v238, v69
	v_mov_b32_e32 v66, v154
	v_mov_b32_e32 v163, v67
	v_mul_f32_e32 v69, v34, v32
	v_pk_add_f32 v[130:131], v[154:155], v[130:131]
	v_pk_mul_f32 v[154:155], v[66:67], v[162:163]
	v_mul_f32_e32 v32, v73, v73
	v_mov_b32_e32 v131, v155
	v_pk_fma_f32 v[154:155], v[72:73], v[72:73], v[32:33] op_sel_hi:[1,1,0]
	v_mov_b32_e32 v162, v156
	v_mov_b32_e32 v68, v154
	v_mov_b32_e32 v163, v69
	v_add_f32_e32 v65, v238, v70
	v_mov_b32_e32 v158, v64
	v_pk_add_f32 v[154:155], v[154:155], v[156:157]
	v_pk_mul_f32 v[156:157], v[68:69], v[162:163]
	v_and_b32_e32 v161, 0xffff0000, v125
	v_add_f32_e32 v127, v238, v71
	v_pk_mul_f32 v[70:71], v[64:65], v[158:159]
	v_mov_b32_e32 v79, v65
	v_mov_b32_e32 v158, v78
	v_mov_b32_e32 v160, v126
	v_mov_b32_e32 v155, v157
	v_pk_mul_f32 v[124:125], v[126:127], v[160:161]
	v_mov_b32_e32 v129, v127
	v_mov_b32_e32 v160, v128
	v_pk_add_f32 v[130:131], v[130:131], v[154:155]
	v_pk_fma_f32 v[154:155], v[78:79], v[158:159], v[70:71]
	v_pk_mul_f32 v[156:157], v[70:71], v[70:71]
	v_pk_mul_f32 v[158:159], v[124:125], v[124:125]
	v_mov_b32_e32 v155, v157
	v_pk_fma_f32 v[156:157], v[128:129], v[160:161], v[124:125]
	v_add_f32_e32 v34, v240, v84
	v_mov_b32_e32 v157, v159
	v_pk_add_f32 v[154:155], v[154:155], v[156:157]
	v_mov_b32_e32 v157, v94
	v_mov_b32_e32 v94, v93
	v_pk_add_f32 v[154:155], v[130:131], v[154:155]
	v_lshlrev_b32_e32 v131, 16, v121
	v_lshlrev_b32_e32 v130, 16, v120
	v_mov_b32_e32 v156, v92
	v_and_b32_e32 v121, 0xffff0000, v121
	v_and_b32_e32 v120, 0xffff0000, v120
	v_pk_add_f32 v[92:93], v[240:241], v[94:95] op_sel_hi:[0,1]
	v_pk_mul_f32 v[92:93], v[92:93], v[120:121]
	v_lshlrev_b32_e32 v120, 16, v118
	v_and_b32_e32 v121, 0xffff0000, v118
	v_lshlrev_b32_e32 v118, 16, v119
	v_and_b32_e32 v119, 0xffff0000, v119
	v_pk_mul_f32 v[90:91], v[90:91], v[118:119]
	v_pk_add_f32 v[156:157], v[240:241], v[156:157] op_sel_hi:[0,1]
	v_mul_f32_e32 v32, v91, v91
	v_pk_fma_f32 v[118:119], v[90:91], v[90:91], v[32:33] op_sel_hi:[1,1,0]
	v_lshlrev_b32_e32 v32, 16, v116
	v_mul_f32_e32 v84, v34, v32
	v_and_b32_e32 v32, 0xffff0000, v116
	v_add_f32_e32 v34, v240, v85
	v_mul_f32_e32 v116, v34, v32
	v_lshlrev_b32_e32 v32, 16, v117
	v_add_f32_e32 v34, v240, v86
	v_pk_mul_f32 v[130:131], v[156:157], v[130:131]
	v_pk_mul_f32 v[94:95], v[92:93], v[92:93]
	v_mul_f32_e32 v86, v34, v32
	v_and_b32_e32 v32, 0xffff0000, v117
	v_add_f32_e32 v34, v240, v87
	v_pk_fma_f32 v[94:95], v[130:131], v[130:131], v[94:95]
	v_pk_mul_f32 v[88:89], v[88:89], v[120:121]
	v_mul_f32_e32 v120, v34, v32
	v_lshlrev_b32_e32 v32, 16, v114
	v_add_f32_e32 v34, v240, v80
	v_pk_add_f32 v[94:95], v[94:95], v[94:95] op_sel:[0,1] op_sel_hi:[1,0]
	v_mul_f32_e32 v157, v34, v32
	v_pk_add_f32 v[154:155], v[154:155], v[154:155] op_sel:[0,1] op_sel_hi:[1,0]
	v_and_b32_e32 v32, 0xffff0000, v114
	v_add_f32_e32 v34, v240, v81
	v_mov_b32_e32 v156, v154
	v_mov_b32_e32 v162, v94
	v_mov_b32_e32 v163, v157
	v_mul_f32_e32 v81, v34, v32
	v_pk_add_f32 v[94:95], v[154:155], v[94:95]
	v_pk_mul_f32 v[154:155], v[156:157], v[162:163]
	v_mul_f32_e32 v32, v89, v89
	v_mov_b32_e32 v95, v155
	v_pk_fma_f32 v[154:155], v[88:89], v[88:89], v[32:33] op_sel_hi:[1,1,0]
	v_mov_b32_e32 v162, v118
	v_mov_b32_e32 v80, v154
	v_mov_b32_e32 v163, v81
	v_lshlrev_b32_e32 v159, 16, v115
	v_add_f32_e32 v85, v240, v82
	v_mov_b32_e32 v158, v84
	v_pk_add_f32 v[118:119], v[154:155], v[118:119]
	v_pk_mul_f32 v[154:155], v[80:81], v[162:163]
	v_and_b32_e32 v115, 0xffff0000, v115
	v_add_f32_e32 v87, v240, v83
	v_pk_mul_f32 v[82:83], v[84:85], v[158:159]
	v_mov_b32_e32 v117, v85
	v_mov_b32_e32 v158, v116
	v_mov_b32_e32 v114, v86
	v_mov_b32_e32 v119, v155
	v_pk_mul_f32 v[160:161], v[86:87], v[114:115]
	v_mov_b32_e32 v121, v87
	v_mov_b32_e32 v114, v120
	v_pk_add_f32 v[94:95], v[94:95], v[118:119]
	v_pk_fma_f32 v[118:119], v[116:117], v[158:159], v[82:83]
	v_pk_mul_f32 v[154:155], v[82:83], v[82:83]
	v_pk_fma_f32 v[114:115], v[120:121], v[114:115], v[160:161]
	v_mov_b32_e32 v119, v155
	v_pk_mul_f32 v[154:155], v[160:161], v[160:161]
	v_and_b32_e32 v37, 64, v245
	v_mov_b32_e32 v115, v155
	v_xor_b32_e32 v34, 16, v245
	v_add_u32_e32 v37, 64, v37
	v_pk_add_f32 v[114:115], v[118:119], v[114:115]
	v_cmp_lt_i32_e32 vcc, v34, v37
	v_pk_add_f32 v[94:95], v[94:95], v[114:115]
	s_nop 0
	v_cndmask_b32_e32 v34, v245, v34, vcc
	v_add_f32_e32 v32, v94, v95
	v_lshlrev_b32_e32 v34, 2, v34
	ds_bpermute_b32 v34, v34, v32
	v_lshl_add_u64 v[94:95], v[112:113], 0, v[208:209]
	v_lshl_add_u64 v[112:113], v[94:95], 0, s[18:19]
	s_waitcnt lgkmcnt(0)
	v_add_f32_e32 v32, v32, v34
	v_xor_b32_e32 v34, 32, v245
	v_cmp_lt_i32_e32 vcc, v34, v37
	s_nop 1
	v_cndmask_b32_e32 v34, v245, v34, vcc
	v_lshlrev_b32_e32 v34, 2, v34
	ds_bpermute_b32 v34, v34, v32
	s_waitcnt lgkmcnt(0)
	v_add_f32_e32 v32, v32, v34
	v_fmamk_f32 v32, v32, 0x3b800000, v244
	v_cmp_gt_f32_e32 vcc, s7, v32
	v_mul_f32_e32 v34, 0x4b800000, v32
	s_nop 0
	v_cndmask_b32_e32 v32, v32, v34, vcc
	v_rsq_f32_e32 v32, v32
	s_nop 0
	v_mul_f32_e32 v34, 0x45800000, v32
	v_cndmask_b32_e32 v34, v32, v34, vcc
	v_mul_f32_e32 v32, v44, v34
	v_mul_f32_e32 v37, v45, v34
	v_cvt_pk_bf16_f32 v44, v32, v37
	v_mul_f32_e32 v32, v46, v34
	v_add_co_u32_e32 v46, vcc, s47, v94
	v_mul_f32_e32 v37, v47, v34
	v_cvt_pk_bf16_f32 v45, v32, v37
	s_nop 0
	v_addc_co_u32_e32 v47, vcc, 0, v95, vcc
	v_mul_f32_e32 v32, v40, v34
	global_store_dwordx2 v[46:47], v[44:45], off offset:1536
	v_mul_f32_e32 v37, v41, v34
	v_cvt_pk_bf16_f32 v40, v32, v37
	v_mul_f32_e32 v32, v42, v34
	v_mul_f32_e32 v37, v43, v34
	v_cvt_pk_bf16_f32 v41, v32, v37
	v_mul_f32_e32 v32, v36, v34
	v_mul_f32_e32 v36, v146, v34
	global_store_dwordx2 v[112:113], v[40:41], off offset:32
	v_cvt_pk_bf16_f32 v36, v32, v36
	v_mul_f32_e32 v32, v38, v34
	v_mul_f32_e32 v37, v148, v34
	v_cvt_pk_bf16_f32 v37, v32, v37
	v_mul_f32_e32 v32, v151, v34
	v_mul_f32_e32 v33, v33, v34
	global_store_dwordx2 v[112:113], v[36:37], off offset:64
	v_cvt_pk_bf16_f32 v32, v32, v33
	v_mul_f32_e32 v33, v35, v34
	v_mul_f32_e32 v35, v145, v34
	v_cvt_pk_bf16_f32 v33, v33, v35
	global_store_dwordx2 v[112:113], v[32:33], off offset:96
	v_mul_f32_e32 v32, v152, v34
	v_mul_f32_e32 v33, v60, v34
	v_cvt_pk_bf16_f32 v32, v32, v33
	v_mul_f32_e32 v33, v153, v34
	v_mul_f32_e32 v35, v61, v34
	v_cvt_pk_bf16_f32 v33, v33, v35
	global_store_dwordx2 v[112:113], v[32:33], off offset:128
	v_mul_f32_e32 v32, v56, v34
	v_mul_f32_e32 v33, v57, v34
	v_cvt_pk_bf16_f32 v32, v32, v33
	v_mul_f32_e32 v33, v58, v34
	v_mul_f32_e32 v35, v59, v34
	v_cvt_pk_bf16_f32 v33, v33, v35
	global_store_dwordx2 v[112:113], v[32:33], off offset:160
	v_mul_f32_e32 v32, v52, v34
	v_mul_f32_e32 v33, v62, v34
	v_cvt_pk_bf16_f32 v32, v32, v33
	v_mul_f32_e32 v33, v136, v34
	v_mul_f32_e32 v35, v138, v34
	v_cvt_pk_bf16_f32 v33, v33, v35
	global_store_dwordx2 v[112:113], v[32:33], off offset:192
	v_mul_f32_e32 v32, v55, v34
	v_mul_f32_e32 v33, v49, v34
	v_cvt_pk_bf16_f32 v32, v32, v33
	v_mul_f32_e32 v33, v51, v34
	v_mul_f32_e32 v35, v135, v34
	v_cvt_pk_bf16_f32 v33, v33, v35
	global_store_dwordx2 v[112:113], v[32:33], off offset:224
	v_mul_f32_e32 v32, v140, v34
	v_mul_f32_e32 v33, v76, v34
	v_cvt_pk_bf16_f32 v32, v32, v33
	v_mul_f32_e32 v33, v141, v34
	v_mul_f32_e32 v35, v77, v34
	v_cvt_pk_bf16_f32 v33, v33, v35
	global_store_dwordx2 v[112:113], v[32:33], off offset:256
	v_mul_f32_e32 v32, v72, v34
	v_mul_f32_e32 v33, v73, v34
	v_cvt_pk_bf16_f32 v32, v32, v33
	v_mul_f32_e32 v33, v74, v34
	v_mul_f32_e32 v35, v75, v34
	v_cvt_pk_bf16_f32 v33, v33, v35
	global_store_dwordx2 v[112:113], v[32:33], off offset:288
	v_mul_f32_e32 v32, v64, v34
	v_mul_f32_e32 v33, v78, v34
	v_cvt_pk_bf16_f32 v32, v32, v33
	v_mul_f32_e32 v33, v126, v34
	v_mul_f32_e32 v35, v128, v34
	v_cvt_pk_bf16_f32 v33, v33, v35
	global_store_dwordx2 v[112:113], v[32:33], off offset:320
	v_mul_f32_e32 v32, v67, v34
	v_mul_f32_e32 v33, v69, v34
	v_cvt_pk_bf16_f32 v32, v32, v33
	v_mul_f32_e32 v33, v71, v34
	v_mul_f32_e32 v35, v125, v34
	v_cvt_pk_bf16_f32 v33, v33, v35
	global_store_dwordx2 v[112:113], v[32:33], off offset:352
	v_mul_f32_e32 v32, v130, v34
	v_mul_f32_e32 v33, v92, v34
	v_cvt_pk_bf16_f32 v32, v32, v33
	v_mul_f32_e32 v33, v131, v34
	v_mul_f32_e32 v35, v93, v34
	v_cvt_pk_bf16_f32 v33, v33, v35
	global_store_dwordx2 v[112:113], v[32:33], off offset:384
	v_mul_f32_e32 v32, v88, v34
	v_mul_f32_e32 v33, v89, v34
	v_cvt_pk_bf16_f32 v32, v32, v33
	v_mul_f32_e32 v33, v90, v34
	v_mul_f32_e32 v35, v91, v34
	v_cvt_pk_bf16_f32 v33, v33, v35
	global_store_dwordx2 v[112:113], v[32:33], off offset:416
	v_mul_f32_e32 v32, v84, v34
	v_mul_f32_e32 v33, v116, v34
	v_cvt_pk_bf16_f32 v32, v32, v33
	v_mul_f32_e32 v33, v86, v34
	v_mul_f32_e32 v35, v120, v34
	v_cvt_pk_bf16_f32 v33, v33, v35
	global_store_dwordx2 v[112:113], v[32:33], off offset:448
	v_mul_f32_e32 v32, v157, v34
	v_mul_f32_e32 v33, v81, v34
	v_cvt_pk_bf16_f32 v32, v32, v33
	v_mul_f32_e32 v33, v83, v34
	v_mul_f32_e32 v34, v161, v34
	v_cvt_pk_bf16_f32 v33, v33, v34
	global_store_dwordx2 v[112:113], v[32:33], off offset:480
	s_barrier
	s_cbranch_scc0 .LBB0_242
